# attention QK nope pairs: first MFMA waits only for its own K fragment (lgkmcnt(1)); MLA pair MFMA order matches read order
# speedup vs baseline: 1.0023x; 1.0023x over previous
; __device__ __forceinline__ void finishSM(f32x16& p0, f32x16& p1, float alpha, float& l_reg, bf16x8& pa0, bf16x8& pa1, bf16x8& pa2, bf16x8& pa3) {
; #pragma unroll
;   for (int r = 0; r < 16; ++r) p1[r] = __builtin_amdgcn_exp2f(p1[r]);
;   float ps = 0;
; #pragma unroll
;   for (int r = 0; r < 16; ++r) ps += p0[r];
; #pragma unroll
;   for (int r = 0; r < 16; ++r) ps += p1[r];
;   { auto rr = __builtin_amdgcn_permlane32_swap(__float_as_uint(ps), __float_as_uint(ps), false, false);
;     ps = __uint_as_float(rr[0]) + __uint_as_float(rr[1]); }
;   l_reg = l_reg * alpha + ps;
;     ...
;   PK4(p0, 0, pa0); PK4(p0, 8, pa1); PK4(p1, 0, pa2); PK4(p1, 8, pa3);
;     ...
; }
; template <bool MLA>
; __device__ __forceinline__ void qkt(f32x16& p0, f32x16& p1, const char* Ks, const char* KRs, const bf16x8* qr, const char* qrl, const f32x16& negm, int r32, int hi) {
; #pragma unroll
;   for (int d0 = 0; d0 < 8; ++d0) { int cb = (d0 * 16 + hi * 8) * 2;
;     bf16x8 b0 = *reinterpret_cast<const bf16x8*>(Ks + KSWZ(r32, cb));
;     bf16x8 b1 = *reinterpret_cast<const bf16x8*>(Ks + KSWZ(32 + r32, cb));
;     if (d0 == 0) { p0 = __builtin_amdgcn_mfma_f32_32x32x16_bf16(b0, qr[0], negm, 0, 0, 0); p1 = __builtin_amdgcn_mfma_f32_32x32x16_bf16(b1, qr[0], negm, 0, 0, 0); }
;     else { p0 = __builtin_amdgcn_mfma_f32_32x32x16_bf16(b0, qr[d0], p0, 0, 0, 0); p1 = __builtin_amdgcn_mfma_f32_32x32x16_bf16(b1, qr[d0], p1, 0, 0, 0); } }
;   if constexpr (MLA) {
; #pragma unroll
;     for (int d0 = 0; d0 < 4; ++d0) { int ch = d0 * 2 + hi;
;       bf16x8 b0 = *reinterpret_cast<const bf16x8*>(KRs + KRSWZ(r32, ch));
;       bf16x8 b1 = *reinterpret_cast<const bf16x8*>(KRs + KRSWZ(32 + r32, ch));
;       const bf16x8 qq = *reinterpret_cast<const bf16x8*>(qrl + d0 * 1024);
;       p0 = __builtin_amdgcn_mfma_f32_32x32x16_bf16(b0, qq, p0, 0, 0, 0);
;       p1 = __builtin_amdgcn_mfma_f32_32x32x16_bf16(b1, qq, p1, 0, 0, 0); }
;   }
.LBB0_101:
	s_mov_b32 s10, s24
	s_mov_b32 s24, s35
	s_lshl_b32 s2, s25, 14
	s_add_i32 s27, s2, 0
	s_add_i32 s32, s27, s15
	s_lshl_b32 s30, s25, 13
	s_lshl_b32 s11, s10, 14
	s_add_i32 s3, s11, 0
	v_add_u32_e32 v0, s3, v210
	ds_read_b128 v[234:237], v0 offset:57344
	ds_read_b128 v[98:101], v0 offset:49152
	v_add_u32_e32 v0, s3, v209
	s_lshl_b32 s2, s10, 13
	s_add_i32 s2, s2, 0
	s_add_i32 s2, s2, 0x18000
	s_add_u32 vcc_lo, s28, s46
	s_addc_u32 vcc_hi, s29, s47
	s_add_i32 m0, s32, 0xc000
	v_lshl_add_u64 v[250:251], v[172:173], 0, vcc
	global_load_lds_dwordx4 v[250:251], off
	v_exp_f32_e32 v213, v82
	v_add_f32_e32 v212, 0, v227
	v_add_f32_e32 v212, v229, v212
	s_waitcnt lgkmcnt(0)
	v_mfma_f32_32x32x16_bf16 v[114:129], v[98:101], v[158:161], v[66:81]
	v_exp_f32_e32 v246, v83
	v_add_f32_e32 v212, v225, v212
	v_add_f32_e32 v212, v228, v212
	s_lshl_b32 s31, s35, 14
	v_mfma_f32_32x32x16_bf16 v[98:113], v[234:237], v[158:161], v[66:81]
	ds_read_b128 v[234:237], v0 offset:57344
	ds_read_b128 v[238:241], v0 offset:49152
	v_add_u32_e32 v0, s3, v208
	s_add_u32 vcc_lo, s28, 0x4380100
	s_addc_u32 vcc_hi, s29, 0
	s_mov_b32 m0, s32
	v_lshl_add_u64 v[250:251], v[170:171], 0, vcc
	global_load_lds_dwordx4 v[250:251], off
	v_exp_f32_e32 v247, v84
	v_add_f32_e32 v212, v224, v212
	v_add_f32_e32 v212, v226, v212
	s_waitcnt lgkmcnt(1)
	v_mfma_f32_32x32x16_bf16 v[98:113], v[234:237], v[154:157], v[98:113]
	v_exp_f32_e32 v249, v85
	v_add_f32_e32 v212, v222, v212
	v_add_f32_e32 v212, v223, v212
	s_waitcnt lgkmcnt(0)
	v_mfma_f32_32x32x16_bf16 v[114:129], v[238:241], v[154:157], v[114:129]
	ds_read_b128 v[234:237], v0 offset:57344
	ds_read_b128 v[238:241], v0 offset:49152
	v_add_u32_e32 v0, s3, v207
	s_add_u32 vcc_lo, s28, s46
	s_addc_u32 vcc_hi, s29, s47
	s_add_i32 m0, s32, 0xc400
	v_lshl_add_u64 v[250:251], v[174:175], 0, vcc
	global_load_lds_dwordx4 v[250:251], off
	v_exp_f32_e32 v252, v86
	v_add_f32_e32 v212, v219, v212
	v_add_f32_e32 v212, v221, v212
	s_waitcnt lgkmcnt(1)
	v_mfma_f32_32x32x16_bf16 v[98:113], v[234:237], v[150:153], v[98:113]
	v_exp_f32_e32 v253, v87
	v_add_f32_e32 v212, v218, v212
	v_add_f32_e32 v212, v220, v212
	s_waitcnt lgkmcnt(0)
	v_mfma_f32_32x32x16_bf16 v[114:129], v[238:241], v[150:153], v[114:129]
	ds_read_b128 v[234:237], v0 offset:57344
	ds_read_b128 v[238:241], v0 offset:49152
	v_add_u32_e32 v0, s3, v206
	s_add_u32 vcc_lo, s28, 0x4380180
	s_addc_u32 vcc_hi, s29, 0
	s_add_i32 m0, s32, 0x400
	v_lshl_add_u64 v[250:251], v[170:171], 0, vcc
	global_load_lds_dwordx4 v[250:251], off
	v_exp_f32_e32 v254, v88
	v_add_f32_e32 v212, v215, v212
	v_add_f32_e32 v212, v217, v212
	s_waitcnt lgkmcnt(1)
	v_mfma_f32_32x32x16_bf16 v[98:113], v[234:237], v[146:149], v[98:113]
	v_exp_f32_e32 v255, v89
	v_add_f32_e32 v212, v214, v212
	v_add_f32_e32 v212, v216, v212
	s_waitcnt lgkmcnt(0)
	v_mfma_f32_32x32x16_bf16 v[114:129], v[238:241], v[146:149], v[114:129]
	ds_read_b128 v[234:237], v0 offset:57344
	ds_read_b128 v[238:241], v0 offset:49152
	v_add_u32_e32 v0, s3, v205
	s_add_u32 vcc_lo, s28, 0x2e340600
	s_addc_u32 vcc_hi, s29, 0
	s_add_i32 m0, s23, s30
	v_lshl_add_u64 v[250:251], v[168:169], 0, vcc
	global_load_lds_dwordx4 v[250:251], off
	v_cvt_pk_bf16_f32 v82, v227, v229
	v_exp_f32_e32 v90, v90
	v_cvt_pk_bf16_f32 v83, v225, v228
	s_waitcnt lgkmcnt(1)
	v_mfma_f32_32x32x16_bf16 v[98:113], v[234:237], v[142:145], v[98:113]
	v_exp_f32_e32 v91, v91
	v_cvt_pk_bf16_f32 v84, v224, v226
	v_exp_f32_e32 v92, v92
	s_waitcnt lgkmcnt(0)
	v_mfma_f32_32x32x16_bf16 v[114:129], v[238:241], v[142:145], v[114:129]
	ds_read_b128 v[234:237], v0 offset:57344
	ds_read_b128 v[238:241], v0 offset:49152
	v_add_u32_e32 v0, s3, v204
	v_cvt_pk_bf16_f32 v85, v222, v223
	v_exp_f32_e32 v93, v93
	v_cvt_pk_bf16_f32 v86, v219, v221
	s_waitcnt lgkmcnt(1)
	v_mfma_f32_32x32x16_bf16 v[98:113], v[234:237], v[138:141], v[98:113]
	v_exp_f32_e32 v94, v94
	v_cvt_pk_bf16_f32 v87, v218, v220
	v_exp_f32_e32 v95, v95
	s_waitcnt lgkmcnt(0)
	v_mfma_f32_32x32x16_bf16 v[114:129], v[238:241], v[138:141], v[114:129]
	ds_read_b128 v[234:237], v0 offset:57344
	ds_read_b128 v[238:241], v0 offset:49152
	v_add_u32_e32 v0, s3, v203
	v_cvt_pk_bf16_f32 v88, v215, v217
	v_exp_f32_e32 v96, v96
	v_cvt_pk_bf16_f32 v89, v214, v216
	s_waitcnt lgkmcnt(1)
	v_mfma_f32_32x32x16_bf16 v[98:113], v[234:237], v[134:137], v[98:113]
	v_exp_f32_e32 v97, v97
	v_add_f32_e32 v212, v213, v212
	v_add_f32_e32 v212, v246, v212
	s_waitcnt lgkmcnt(0)
	v_mfma_f32_32x32x16_bf16 v[114:129], v[238:241], v[134:137], v[114:129]
	ds_read_b128 v[234:237], v0 offset:57344
	ds_read_b128 v[238:241], v0 offset:49152
	v_add_u32_e32 v0, s2, v200
	v_add_f32_e32 v212, v247, v212
	v_add_f32_e32 v212, v249, v212
	v_add_f32_e32 v212, v252, v212
	s_waitcnt lgkmcnt(1)
	v_mfma_f32_32x32x16_bf16 v[98:113], v[234:237], v[130:133], v[98:113]
	v_add_f32_e32 v212, v253, v212
	v_add_f32_e32 v212, v254, v212
	v_add_f32_e32 v212, v255, v212
	s_waitcnt lgkmcnt(0)
	v_mfma_f32_32x32x16_bf16 v[114:129], v[238:241], v[130:133], v[114:129]
	ds_read_b128 v[234:237], v0
	ds_read_b128 v[238:241], v0 offset:4096
	ds_read_b128 v[242:245], v198
	v_add_u32_e32 v0, s2, v201
	v_add_f32_e32 v212, v90, v212
	v_add_f32_e32 v212, v91, v212
	s_waitcnt lgkmcnt(0)
	v_mfma_f32_32x32x16_bf16 v[114:129], v[234:237], v[242:245], v[114:129]
	v_add_f32_e32 v212, v92, v212
	v_add_f32_e32 v212, v93, v212
	v_mfma_f32_32x32x16_bf16 v[98:113], v[238:241], v[242:245], v[98:113]
	ds_read_b128 v[234:237], v0
	ds_read_b128 v[238:241], v0 offset:4096
	ds_read_b128 v[242:245], v198 offset:1024
	v_add_u32_e32 v0, s2, v199
	v_add_f32_e32 v212, v94, v212
	v_add_f32_e32 v212, v95, v212
	s_waitcnt lgkmcnt(0)
; template <bool FIRST, bool MLA>
; __device__ __forceinline__ void partialSM(f32x16& p0, f32x16& p1, f32x16& negm, float& m_reg, float& alpha) {
;   float a = max3f(p0[0], p0[1], p1[0]), b = max3f(p0[2], p0[3], p1[1]); a = max3f(a, p1[2], p1[3]);
; #pragma unroll
;   for (int r = 4; r < 16; r += 4) { a = max3f(a, p0[r], p0[r + 1]); b = max3f(b, p0[r + 2], p0[r + 3]); a = max3f(a, p1[r], p1[r + 1]); b = max3f(b, p1[r + 2], p1[r + 3]); }
;   float pmax = fmaxf(a, b);
;   { auto rr = __builtin_amdgcn_permlane32_swap(__float_as_uint(pmax), __float_as_uint(pmax), false, false);
;     pmax = fmaxf(__uint_as_float(rr[0]), __uint_as_float(rr[1])); }
;   alpha = 1.f;
;   if constexpr (MLA) {
;     if (FIRST) m_reg = pmax;
;     else if (!__builtin_expect(__all(pmax - m_reg <= THR2), 1)) { const float mn = fmaxf(m_reg, pmax); alpha = __builtin_amdgcn_exp2f(m_reg - mn); m_reg = mn; }
; #pragma unroll
;     for (int r = 0; r < 16; ++r) { p0[r] -= m_reg; p1[r] -= m_reg; }
;   } else
;   if (FIRST || __builtin_expect(__any(pmax > THR2), 0)) {
; template <bool MLA>
; __device__ __forceinline__ void qkt(f32x16& p0, f32x16& p1, const char* Ks, const char* KRs, const bf16x8* qr, const char* qrl, const f32x16& negm, int r32, int hi) {
;     ...
;   if constexpr (MLA) {
; #pragma unroll
;     for (int d0 = 0; d0 < 4; ++d0) { int ch = d0 * 2 + hi;
;       bf16x8 b0 = *reinterpret_cast<const bf16x8*>(KRs + KRSWZ(r32, ch));
;       bf16x8 b1 = *reinterpret_cast<const bf16x8*>(KRs + KRSWZ(32 + r32, ch));
;       const bf16x8 qq = *reinterpret_cast<const bf16x8*>(qrl + d0 * 1024);
;       p0 = __builtin_amdgcn_mfma_f32_32x32x16_bf16(b0, qq, p0, 0, 0, 0);
;       p1 = __builtin_amdgcn_mfma_f32_32x32x16_bf16(b1, qq, p1, 0, 0, 0); }
;   }
; }
; __device__ __forceinline__ int v_st(int k, int c) { const int kk = (k & ~0xC) | ((k & 4) << 1) | ((k & 8) >> 1); return ((kk >> 3) * 4 + (c >> 5)) * 512 + ((kk & 7) * 32 + (c & 31)) * 2; }
; __device__ __forceinline__ int v_rd_base(int lane) { return ((lane & 3) << 3) | (((lane >> 2) & 3) << 6) | (((lane >> 4) & 1) << 5) | (((lane >> 5) & 1) << 8); }
; template <int OFF> __device__ __forceinline__ s16x4 tr_read(int vb) {
;   s16x4 r; asm volatile("ds_read_b64_tr_b16 %0, %1 offset:%2" : "=&v"(r) : "v"(vb), "i"(OFF) : "memory"); return r;
; }
	v_mfma_f32_32x32x16_bf16 v[114:129], v[234:237], v[242:245], v[114:129]
	v_add_f32_e32 v212, v96, v212
	v_add_f32_e32 v212, v97, v212
	v_mfma_f32_32x32x16_bf16 v[98:113], v[238:241], v[242:245], v[98:113]
	ds_read_b128 v[234:237], v0
	ds_read_b128 v[238:241], v0 offset:4096
	ds_read_b128 v[242:245], v198 offset:2048
	v_add_u32_e32 v0, s2, v202
	v_cvt_pk_bf16_f32 v97, v96, v97
	v_cvt_pk_bf16_f32 v96, v94, v95
	s_waitcnt lgkmcnt(0)
	v_mfma_f32_32x32x16_bf16 v[114:129], v[234:237], v[242:245], v[114:129]
	v_cvt_pk_bf16_f32 v95, v92, v93
	v_cvt_pk_bf16_f32 v94, v90, v91
	v_mfma_f32_32x32x16_bf16 v[98:113], v[238:241], v[242:245], v[98:113]
	ds_read_b128 v[234:237], v0
	ds_read_b128 v[238:241], v0 offset:4096
	ds_read_b128 v[242:245], v198 offset:3072
	v_cvt_pk_bf16_f32 v90, v213, v246
	v_cvt_pk_bf16_f32 v91, v247, v249
	s_waitcnt lgkmcnt(0)
	v_mfma_f32_32x32x16_bf16 v[114:129], v[234:237], v[242:245], v[114:129]
	v_cvt_pk_bf16_f32 v92, v252, v253
	v_cvt_pk_bf16_f32 v93, v254, v255
	v_mfma_f32_32x32x16_bf16 v[98:113], v[238:241], v[242:245], v[98:113]
	v_add_u32_e32 v213, s31, v197
	ds_read_b64_tr_b16 v[214:215], v213 offset:0
	ds_read_b64_tr_b16 v[216:217], v213 offset:0x800
	ds_read_b64_tr_b16 v[218:219], v213 offset:0x1000
	ds_read_b64_tr_b16 v[220:221], v213 offset:0x1800
	ds_read_b64_tr_b16 v[222:223], v213 offset:0x2000
	ds_read_b64_tr_b16 v[224:225], v213 offset:0x2800
	ds_read_b64_tr_b16 v[226:227], v213 offset:0x3000
	ds_read_b64_tr_b16 v[228:229], v213 offset:0x3800
	s_waitcnt lgkmcnt(0)
	v_mov_b32_e32 v0, v212
	s_nop 1
	v_permlane32_swap_b32_e32 v0, v212
	v_permlane32_swap_b32_e32 v82, v84
	v_permlane32_swap_b32_e32 v83, v85
	v_permlane32_swap_b32_e32 v86, v88
	v_permlane32_swap_b32_e32 v87, v89
	v_permlane32_swap_b32_e32 v90, v92
	v_permlane32_swap_b32_e32 v91, v93
	v_permlane32_swap_b32_e32 v94, v96
	v_permlane32_swap_b32_e32 v95, v97
	v_mfma_f32_32x32x16_bf16 v[50:65], v[82:85], v[214:217], v[50:65]
	ds_read_b64_tr_b16 v[214:215], v213 offset:0x200
	ds_read_b64_tr_b16 v[216:217], v213 offset:0xa00
	v_mfma_f32_32x32x16_bf16 v[50:65], v[86:89], v[218:221], v[50:65]
	ds_read_b64_tr_b16 v[218:219], v213 offset:0x1200
	ds_read_b64_tr_b16 v[220:221], v213 offset:0x1a00
	v_mfma_f32_32x32x16_bf16 v[50:65], v[90:93], v[222:225], v[50:65]
	ds_read_b64_tr_b16 v[222:223], v213 offset:0x2200
	ds_read_b64_tr_b16 v[224:225], v213 offset:0x2a00
	v_mfma_f32_32x32x16_bf16 v[50:65], v[94:97], v[226:229], v[50:65]
	ds_read_b64_tr_b16 v[226:227], v213 offset:0x3200
	ds_read_b64_tr_b16 v[228:229], v213 offset:0x3a00
	s_waitcnt lgkmcnt(6)
	v_mfma_f32_32x32x16_bf16 v[34:49], v[82:85], v[214:217], v[34:49]
	ds_read_b64_tr_b16 v[214:215], v213 offset:0x400
	ds_read_b64_tr_b16 v[216:217], v213 offset:0xc00
	s_waitcnt lgkmcnt(6)
	v_mfma_f32_32x32x16_bf16 v[34:49], v[86:89], v[218:221], v[34:49]
	ds_read_b64_tr_b16 v[218:219], v213 offset:0x1400
	ds_read_b64_tr_b16 v[220:221], v213 offset:0x1c00
	s_waitcnt lgkmcnt(6)
	v_mfma_f32_32x32x16_bf16 v[34:49], v[90:93], v[222:225], v[34:49]
	ds_read_b64_tr_b16 v[222:223], v213 offset:0x2400
	ds_read_b64_tr_b16 v[224:225], v213 offset:0x2c00
	s_waitcnt lgkmcnt(6)
	v_mfma_f32_32x32x16_bf16 v[34:49], v[94:97], v[226:229], v[34:49]
	ds_read_b64_tr_b16 v[226:227], v213 offset:0x3400
	ds_read_b64_tr_b16 v[228:229], v213 offset:0x3c00
	s_waitcnt lgkmcnt(6)
	v_mfma_f32_32x32x16_bf16 v[18:33], v[82:85], v[214:217], v[18:33]
	ds_read_b64_tr_b16 v[214:215], v213 offset:0x600
	ds_read_b64_tr_b16 v[216:217], v213 offset:0xe00
	s_waitcnt lgkmcnt(6)
	v_mfma_f32_32x32x16_bf16 v[18:33], v[86:89], v[218:221], v[18:33]
	ds_read_b64_tr_b16 v[218:219], v213 offset:0x1600
	ds_read_b64_tr_b16 v[220:221], v213 offset:0x1e00
	s_waitcnt lgkmcnt(6)
	v_mfma_f32_32x32x16_bf16 v[18:33], v[90:93], v[222:225], v[18:33]
	ds_read_b64_tr_b16 v[222:223], v213 offset:0x2600
	ds_read_b64_tr_b16 v[224:225], v213 offset:0x2e00
	s_waitcnt lgkmcnt(6)
	v_mfma_f32_32x32x16_bf16 v[18:33], v[94:97], v[226:229], v[18:33]
	ds_read_b64_tr_b16 v[226:227], v213 offset:0x3600
	ds_read_b64_tr_b16 v[228:229], v213 offset:0x3e00
	s_waitcnt lgkmcnt(6)
	v_mfma_f32_32x32x16_bf16 v[2:17], v[82:85], v[214:217], v[2:17]
	v_max_f32_e32 v82, v115, v115
	v_max_f32_e32 v83, v114, v114
	v_max_f32_e32 v82, v83, v82
	v_max3_f32 v83, v116, v117, v99
	v_max3_f32 v82, v82, v98, v100
	v_max3_f32 v82, v82, v101, v118
	v_max3_f32 v83, v83, v120, v121
	s_waitcnt lgkmcnt(4)
	v_mfma_f32_32x32x16_bf16 v[2:17], v[86:89], v[218:221], v[2:17]
	v_max3_f32 v82, v82, v119, v102
	v_max3_f32 v83, v83, v104, v105
	v_max3_f32 v82, v82, v103, v122
	v_max3_f32 v83, v83, v124, v125
	v_max3_f32 v82, v82, v123, v106
	v_max3_f32 v83, v83, v108, v109
	v_max3_f32 v82, v82, v107, v126
	s_waitcnt lgkmcnt(2)
	v_mfma_f32_32x32x16_bf16 v[2:17], v[90:93], v[222:225], v[2:17]
	v_max3_f32 v83, v83, v128, v129
	v_max3_f32 v82, v82, v127, v110
	v_max3_f32 v83, v83, v112, v113
	v_max3_f32 v82, v82, v111, v83
	v_mov_b32_e32 v83, v82
	s_nop 1
	v_permlane32_swap_b32_e32 v82, v83
	s_waitcnt lgkmcnt(0)
	v_mfma_f32_32x32x16_bf16 v[2:17], v[94:97], v[226:229], v[2:17]
	v_max_f32_e32 v83, v83, v83
	v_max_f32_e32 v82, v82, v82
	v_max_f32_e32 v82, v82, v83
	v_cmp_lt_f32_e32 vcc, s40, v82
	s_cbranch_vccnz .LBB0_113
	v_mov_b32_e32 v213, 1.0
	v_cmp_gt_f32_e32 vcc, 1.0, v213
	s_cbranch_vccz .LBB0_106

; __device__ __forceinline__ void finishSM(f32x16& p0, f32x16& p1, float alpha, float& l_reg, bf16x8& pa0, bf16x8& pa1, bf16x8& pa2, bf16x8& pa3) {
; #pragma unroll
;   for (int r = 0; r < 16; ++r) p1[r] = __builtin_amdgcn_exp2f(p1[r]);
;   float ps = 0;
; #pragma unroll
;   for (int r = 0; r < 16; ++r) ps += p0[r];
; #pragma unroll
;   for (int r = 0; r < 16; ++r) ps += p1[r];
;   { auto rr = __builtin_amdgcn_permlane32_swap(__float_as_uint(ps), __float_as_uint(ps), false, false);
;     ps = __uint_as_float(rr[0]) + __uint_as_float(rr[1]); }
;   l_reg = l_reg * alpha + ps;
;     ...
;   PK4(p0, 0, pa0); PK4(p0, 8, pa1); PK4(p1, 0, pa2); PK4(p1, 8, pa3);
;     ...
; }
; template <bool MLA>
; __device__ __forceinline__ void qkt(f32x16& p0, f32x16& p1, const char* Ks, const char* KRs, const bf16x8* qr, const char* qrl, const f32x16& negm, int r32, int hi) {
; #pragma unroll
;   for (int d0 = 0; d0 < 8; ++d0) { int cb = (d0 * 16 + hi * 8) * 2;
;     bf16x8 b0 = *reinterpret_cast<const bf16x8*>(Ks + KSWZ(r32, cb));
;     bf16x8 b1 = *reinterpret_cast<const bf16x8*>(Ks + KSWZ(32 + r32, cb));
;     if (d0 == 0) { p0 = __builtin_amdgcn_mfma_f32_32x32x16_bf16(b0, qr[0], negm, 0, 0, 0); p1 = __builtin_amdgcn_mfma_f32_32x32x16_bf16(b1, qr[0], negm, 0, 0, 0); }
;     else { p0 = __builtin_amdgcn_mfma_f32_32x32x16_bf16(b0, qr[d0], p0, 0, 0, 0); p1 = __builtin_amdgcn_mfma_f32_32x32x16_bf16(b1, qr[d0], p1, 0, 0, 0); } }
;   if constexpr (MLA) {
; #pragma unroll
;     for (int d0 = 0; d0 < 4; ++d0) { int ch = d0 * 2 + hi;
;       bf16x8 b0 = *reinterpret_cast<const bf16x8*>(KRs + KRSWZ(r32, ch));
;       bf16x8 b1 = *reinterpret_cast<const bf16x8*>(KRs + KRSWZ(32 + r32, ch));
;       const bf16x8 qq = *reinterpret_cast<const bf16x8*>(qrl + d0 * 1024);
;       p0 = __builtin_amdgcn_mfma_f32_32x32x16_bf16(b0, qq, p0, 0, 0, 0);
;       p1 = __builtin_amdgcn_mfma_f32_32x32x16_bf16(b1, qq, p1, 0, 0, 0); }
;   }
.LBB0_106:
	s_waitcnt vmcnt(0)
	v_exp_f32_e32 v218, v114
	v_exp_f32_e32 v219, v115
	v_exp_f32_e32 v220, v116
	v_exp_f32_e32 v221, v117
	v_exp_f32_e32 v222, v118
	v_exp_f32_e32 v223, v119
	v_exp_f32_e32 v224, v120
	v_exp_f32_e32 v225, v121
	v_exp_f32_e32 v226, v122
	v_exp_f32_e32 v227, v123
	v_exp_f32_e32 v228, v124
	v_exp_f32_e32 v229, v125
	v_exp_f32_e32 v234, v126
	v_exp_f32_e32 v235, v127
	v_exp_f32_e32 v236, v128
	v_exp_f32_e32 v237, v129
	s_waitcnt vmcnt(0)
	s_barrier
	s_add_i32 s31, s19, s31
	v_add_u32_e32 v82, s27, v210
	ds_read_b128 v[176:179], v82 offset:57344
	ds_read_b128 v[82:85], v82 offset:49152
	v_add_u32_e32 v180, s27, v209
	s_add_i32 s2, s30, 0
	s_add_i32 s2, s2, 0x18000
	s_add_u32 vcc_lo, s28, s48
	s_addc_u32 vcc_hi, s29, s49
	s_add_i32 m0, s31, 0xc000
	v_lshl_add_u64 v[250:251], v[172:173], 0, vcc
	global_load_lds_dwordx4 v[250:251], off
	v_exp_f32_e32 v238, v100
	v_add_f32_e32 v255, 0, v218
	v_add_f32_e32 v255, v219, v255
	s_waitcnt lgkmcnt(0)
	v_mfma_f32_32x32x16_bf16 v[114:129], v[82:85], v[158:161], v[66:81]
	v_exp_f32_e32 v239, v101
	v_add_f32_e32 v255, v220, v255
	v_add_f32_e32 v255, v221, v255
	v_mfma_f32_32x32x16_bf16 v[82:97], v[176:179], v[158:161], v[66:81]
	ds_read_b128 v[176:179], v180 offset:57344
	ds_read_b128 v[180:183], v180 offset:49152
	s_add_u32 vcc_lo, s28, 0x43c0100
	s_addc_u32 vcc_hi, s29, 0
	s_mov_b32 m0, s31
	v_lshl_add_u64 v[250:251], v[170:171], 0, vcc
	global_load_lds_dwordx4 v[250:251], off
	v_exp_f32_e32 v246, v102
	v_add_f32_e32 v255, v222, v255
	v_add_f32_e32 v255, v223, v255
	s_waitcnt lgkmcnt(1)
	v_mfma_f32_32x32x16_bf16 v[82:97], v[176:179], v[154:157], v[82:97]
	v_exp_f32_e32 v247, v103
	v_add_f32_e32 v255, v224, v255
	v_add_f32_e32 v255, v225, v255
	s_waitcnt lgkmcnt(0)
	v_mfma_f32_32x32x16_bf16 v[114:129], v[180:183], v[154:157], v[114:129]
	v_add_u32_e32 v180, s27, v208
	ds_read_b128 v[176:179], v180 offset:57344
	ds_read_b128 v[180:183], v180 offset:49152
	s_add_u32 vcc_lo, s28, s48
	s_addc_u32 vcc_hi, s29, s49
	s_add_i32 m0, s31, 0xc400
	v_lshl_add_u64 v[250:251], v[174:175], 0, vcc
	global_load_lds_dwordx4 v[250:251], off
	v_exp_f32_e32 v249, v104
	v_add_f32_e32 v255, v226, v255
	v_add_f32_e32 v255, v227, v255
	s_waitcnt lgkmcnt(1)
	v_mfma_f32_32x32x16_bf16 v[82:97], v[176:179], v[150:153], v[82:97]
	v_exp_f32_e32 v252, v105
	v_add_f32_e32 v255, v228, v255
	v_add_f32_e32 v255, v229, v255
	s_waitcnt lgkmcnt(0)
	v_mfma_f32_32x32x16_bf16 v[114:129], v[180:183], v[150:153], v[114:129]
	v_add_u32_e32 v180, s27, v207
	ds_read_b128 v[176:179], v180 offset:57344
	ds_read_b128 v[180:183], v180 offset:49152
	s_add_u32 vcc_lo, s28, 0x43c0180
	s_addc_u32 vcc_hi, s29, 0
	s_add_i32 m0, s31, 0x400
	v_lshl_add_u64 v[250:251], v[170:171], 0, vcc
	global_load_lds_dwordx4 v[250:251], off
	v_exp_f32_e32 v253, v106
	v_add_f32_e32 v255, v234, v255
	v_add_f32_e32 v255, v235, v255
	s_waitcnt lgkmcnt(1)
	v_mfma_f32_32x32x16_bf16 v[82:97], v[176:179], v[146:149], v[82:97]
	v_exp_f32_e32 v254, v107
	v_add_f32_e32 v255, v236, v255
	v_add_f32_e32 v255, v237, v255
	s_waitcnt lgkmcnt(0)
	v_mfma_f32_32x32x16_bf16 v[114:129], v[180:183], v[146:149], v[114:129]
	v_add_u32_e32 v180, s27, v206
	ds_read_b128 v[176:179], v180 offset:57344
	ds_read_b128 v[180:183], v180 offset:49152
	s_lshl_b32 s32, s24, 13
	s_add_u32 vcc_lo, s28, 0x2e360600
	s_addc_u32 vcc_hi, s29, 0
	s_add_i32 m0, s23, s32
	v_lshl_add_u64 v[250:251], v[168:169], 0, vcc
	global_load_lds_dwordx4 v[250:251], off
	v_cvt_pk_bf16_f32 v100, v218, v219
	v_exp_f32_e32 v98, v98
	s_waitcnt lgkmcnt(1)
	v_mfma_f32_32x32x16_bf16 v[82:97], v[176:179], v[142:145], v[82:97]
	v_cvt_pk_bf16_f32 v101, v220, v221
	v_exp_f32_e32 v99, v99
	s_waitcnt lgkmcnt(0)
	v_mfma_f32_32x32x16_bf16 v[114:129], v[180:183], v[142:145], v[114:129]
	v_add_u32_e32 v180, s27, v205
	ds_read_b128 v[176:179], v180 offset:57344
	ds_read_b128 v[180:183], v180 offset:49152
	v_cvt_pk_bf16_f32 v102, v222, v223
	v_exp_f32_e32 v108, v108
	s_waitcnt lgkmcnt(1)
	v_mfma_f32_32x32x16_bf16 v[82:97], v[176:179], v[138:141], v[82:97]
	v_cvt_pk_bf16_f32 v103, v224, v225
	v_exp_f32_e32 v109, v109
	s_waitcnt lgkmcnt(0)
	v_mfma_f32_32x32x16_bf16 v[114:129], v[180:183], v[138:141], v[114:129]
	v_add_u32_e32 v180, s27, v204
	ds_read_b128 v[176:179], v180 offset:57344
	ds_read_b128 v[180:183], v180 offset:49152
	v_cvt_pk_bf16_f32 v104, v226, v227
	v_exp_f32_e32 v110, v110
	s_waitcnt lgkmcnt(1)
	v_mfma_f32_32x32x16_bf16 v[82:97], v[176:179], v[134:137], v[82:97]
	v_cvt_pk_bf16_f32 v105, v228, v229
	v_exp_f32_e32 v111, v111
	s_waitcnt lgkmcnt(0)
	v_mfma_f32_32x32x16_bf16 v[114:129], v[180:183], v[134:137], v[114:129]
	v_add_u32_e32 v180, s27, v203
	ds_read_b128 v[176:179], v180 offset:57344
	ds_read_b128 v[180:183], v180 offset:49152
	v_cvt_pk_bf16_f32 v106, v234, v235
	v_exp_f32_e32 v112, v112
	s_waitcnt lgkmcnt(1)
	v_mfma_f32_32x32x16_bf16 v[82:97], v[176:179], v[130:133], v[82:97]
	v_cvt_pk_bf16_f32 v107, v236, v237
	v_exp_f32_e32 v113, v113
	s_waitcnt lgkmcnt(0)
	v_mfma_f32_32x32x16_bf16 v[114:129], v[180:183], v[130:133], v[114:129]
	v_add_u32_e32 v180, s2, v200
	ds_read_b128 v[176:179], v180
	ds_read_b128 v[180:183], v180 offset:4096
	ds_read_b128 v[214:217], v198
	v_add_f32_e32 v255, v98, v255
	v_add_f32_e32 v255, v99, v255
	s_waitcnt lgkmcnt(0)
	v_mfma_f32_32x32x16_bf16 v[114:129], v[176:179], v[214:217], v[114:129]
	v_add_f32_e32 v255, v238, v255
	v_add_f32_e32 v255, v239, v255
	v_mfma_f32_32x32x16_bf16 v[82:97], v[180:183], v[214:217], v[82:97]
	v_add_u32_e32 v180, s2, v201
	ds_read_b128 v[176:179], v180
	ds_read_b128 v[180:183], v180 offset:4096
	ds_read_b128 v[214:217], v198 offset:1024
	v_add_f32_e32 v255, v246, v255
	v_add_f32_e32 v255, v247, v255
	s_waitcnt lgkmcnt(0)
; template <bool FIRST, bool MLA>
; __device__ __forceinline__ void partialSM(f32x16& p0, f32x16& p1, f32x16& negm, float& m_reg, float& alpha) {
;   float a = max3f(p0[0], p0[1], p1[0]), b = max3f(p0[2], p0[3], p1[1]); a = max3f(a, p1[2], p1[3]);
; #pragma unroll
;   for (int r = 4; r < 16; r += 4) { a = max3f(a, p0[r], p0[r + 1]); b = max3f(b, p0[r + 2], p0[r + 3]); a = max3f(a, p1[r], p1[r + 1]); b = max3f(b, p1[r + 2], p1[r + 3]); }
;   float pmax = fmaxf(a, b);
;   { auto rr = __builtin_amdgcn_permlane32_swap(__float_as_uint(pmax), __float_as_uint(pmax), false, false);
;     pmax = fmaxf(__uint_as_float(rr[0]), __uint_as_float(rr[1])); }
;   alpha = 1.f;
;   if constexpr (MLA) {
;     if (FIRST) m_reg = pmax;
;     else if (!__builtin_expect(__all(pmax - m_reg <= THR2), 1)) { const float mn = fmaxf(m_reg, pmax); alpha = __builtin_amdgcn_exp2f(m_reg - mn); m_reg = mn; }
; #pragma unroll
;     for (int r = 0; r < 16; ++r) { p0[r] -= m_reg; p1[r] -= m_reg; }
;   } else
;   if (FIRST || __builtin_expect(__any(pmax > THR2), 0)) {
; template <bool MLA>
; __device__ __forceinline__ void qkt(f32x16& p0, f32x16& p1, const char* Ks, const char* KRs, const bf16x8* qr, const char* qrl, const f32x16& negm, int r32, int hi) {
;     ...
;   if constexpr (MLA) {
; #pragma unroll
;     for (int d0 = 0; d0 < 4; ++d0) { int ch = d0 * 2 + hi;
;       bf16x8 b0 = *reinterpret_cast<const bf16x8*>(KRs + KRSWZ(r32, ch));
;       bf16x8 b1 = *reinterpret_cast<const bf16x8*>(KRs + KRSWZ(32 + r32, ch));
;       const bf16x8 qq = *reinterpret_cast<const bf16x8*>(qrl + d0 * 1024);
;       p0 = __builtin_amdgcn_mfma_f32_32x32x16_bf16(b0, qq, p0, 0, 0, 0);
;       p1 = __builtin_amdgcn_mfma_f32_32x32x16_bf16(b1, qq, p1, 0, 0, 0); }
;   }
; }
; __device__ __forceinline__ int v_st(int k, int c) { const int kk = (k & ~0xC) | ((k & 4) << 1) | ((k & 8) >> 1); return ((kk >> 3) * 4 + (c >> 5)) * 512 + ((kk & 7) * 32 + (c & 31)) * 2; }
; __device__ __forceinline__ int v_rd_base(int lane) { return ((lane & 3) << 3) | (((lane >> 2) & 3) << 6) | (((lane >> 4) & 1) << 5) | (((lane >> 5) & 1) << 8); }
; template <int OFF> __device__ __forceinline__ s16x4 tr_read(int vb) {
;   s16x4 r; asm volatile("ds_read_b64_tr_b16 %0, %1 offset:%2" : "=&v"(r) : "v"(vb), "i"(OFF) : "memory"); return r;
; }
	v_mfma_f32_32x32x16_bf16 v[114:129], v[176:179], v[214:217], v[114:129]
	v_add_f32_e32 v255, v249, v255
	v_add_f32_e32 v255, v252, v255
	v_mfma_f32_32x32x16_bf16 v[82:97], v[180:183], v[214:217], v[82:97]
	v_add_u32_e32 v180, s2, v199
	ds_read_b128 v[176:179], v180
	ds_read_b128 v[180:183], v180 offset:4096
	ds_read_b128 v[214:217], v198 offset:2048
	v_add_f32_e32 v255, v253, v255
	v_add_f32_e32 v255, v254, v255
	s_waitcnt lgkmcnt(0)
	v_mfma_f32_32x32x16_bf16 v[114:129], v[176:179], v[214:217], v[114:129]
	v_add_f32_e32 v255, v108, v255
	v_add_f32_e32 v255, v109, v255
	v_mfma_f32_32x32x16_bf16 v[82:97], v[180:183], v[214:217], v[82:97]
	v_add_u32_e32 v180, s2, v202
	ds_read_b128 v[176:179], v180
	ds_read_b128 v[180:183], v180 offset:4096
	ds_read_b128 v[214:217], v198 offset:3072
	v_add_f32_e32 v255, v110, v255
	v_add_f32_e32 v255, v111, v255
	s_waitcnt lgkmcnt(0)
	v_mfma_f32_32x32x16_bf16 v[114:129], v[176:179], v[214:217], v[114:129]
	v_add_f32_e32 v255, v112, v255
	v_add_f32_e32 v255, v113, v255
	v_mfma_f32_32x32x16_bf16 v[82:97], v[180:183], v[214:217], v[82:97]
	v_cvt_pk_bf16_f32 v176, v253, v254
	v_cvt_pk_bf16_f32 v177, v108, v109
	v_cvt_pk_bf16_f32 v178, v110, v111
	v_cvt_pk_bf16_f32 v179, v112, v113
	v_cvt_pk_bf16_f32 v108, v98, v99
	v_cvt_pk_bf16_f32 v109, v238, v239
	v_cvt_pk_bf16_f32 v110, v246, v247
	v_cvt_pk_bf16_f32 v111, v249, v252
	v_mov_b32_e32 v98, v255
	v_add_u32_e32 v112, s11, v197
	ds_read_b64_tr_b16 v[180:181], v112 offset:0
	ds_read_b64_tr_b16 v[182:183], v112 offset:0x800
	ds_read_b64_tr_b16 v[214:215], v112 offset:0x1000
	ds_read_b64_tr_b16 v[216:217], v112 offset:0x1800
	ds_read_b64_tr_b16 v[218:219], v112 offset:0x2000
	ds_read_b64_tr_b16 v[220:221], v112 offset:0x2800
	ds_read_b64_tr_b16 v[222:223], v112 offset:0x3000
	ds_read_b64_tr_b16 v[224:225], v112 offset:0x3800
	s_waitcnt lgkmcnt(0)
	v_mov_b32_e32 v99, v98
	s_nop 1
	v_permlane32_swap_b32_e32 v98, v99
	v_permlane32_swap_b32_e32 v100, v102
	v_permlane32_swap_b32_e32 v176, v178
	v_permlane32_swap_b32_e32 v101, v103
	v_permlane32_swap_b32_e32 v104, v106
	v_permlane32_swap_b32_e32 v105, v107
	v_permlane32_swap_b32_e32 v108, v110
	v_permlane32_swap_b32_e32 v109, v111
	v_permlane32_swap_b32_e32 v177, v179
	v_mfma_f32_32x32x16_bf16 v[50:65], v[100:103], v[180:183], v[50:65]
	ds_read_b64_tr_b16 v[180:181], v112 offset:0x200
	ds_read_b64_tr_b16 v[182:183], v112 offset:0xa00
	v_mfma_f32_32x32x16_bf16 v[50:65], v[104:107], v[214:217], v[50:65]
	ds_read_b64_tr_b16 v[214:215], v112 offset:0x1200
	ds_read_b64_tr_b16 v[216:217], v112 offset:0x1a00
	v_mfma_f32_32x32x16_bf16 v[50:65], v[108:111], v[218:221], v[50:65]
	ds_read_b64_tr_b16 v[218:219], v112 offset:0x2200
	ds_read_b64_tr_b16 v[220:221], v112 offset:0x2a00
	v_mfma_f32_32x32x16_bf16 v[50:65], v[176:179], v[222:225], v[50:65]
	ds_read_b64_tr_b16 v[222:223], v112 offset:0x3200
	ds_read_b64_tr_b16 v[224:225], v112 offset:0x3a00
	s_waitcnt lgkmcnt(6)
	v_mfma_f32_32x32x16_bf16 v[34:49], v[100:103], v[180:183], v[34:49]
	ds_read_b64_tr_b16 v[180:181], v112 offset:0x400
	ds_read_b64_tr_b16 v[182:183], v112 offset:0xc00
	s_waitcnt lgkmcnt(6)
	v_mfma_f32_32x32x16_bf16 v[34:49], v[104:107], v[214:217], v[34:49]
	ds_read_b64_tr_b16 v[214:215], v112 offset:0x1400
	ds_read_b64_tr_b16 v[216:217], v112 offset:0x1c00
	s_waitcnt lgkmcnt(6)
	v_mfma_f32_32x32x16_bf16 v[34:49], v[108:111], v[218:221], v[34:49]
	ds_read_b64_tr_b16 v[218:219], v112 offset:0x2400
	ds_read_b64_tr_b16 v[220:221], v112 offset:0x2c00
	s_waitcnt lgkmcnt(6)
	v_mfma_f32_32x32x16_bf16 v[34:49], v[176:179], v[222:225], v[34:49]
	ds_read_b64_tr_b16 v[222:223], v112 offset:0x3400
	ds_read_b64_tr_b16 v[224:225], v112 offset:0x3c00
	s_waitcnt lgkmcnt(6)
	v_mfma_f32_32x32x16_bf16 v[18:33], v[100:103], v[180:183], v[18:33]
	ds_read_b64_tr_b16 v[180:181], v112 offset:0x600
	ds_read_b64_tr_b16 v[182:183], v112 offset:0xe00
	s_waitcnt lgkmcnt(6)
	v_mfma_f32_32x32x16_bf16 v[18:33], v[104:107], v[214:217], v[18:33]
	ds_read_b64_tr_b16 v[214:215], v112 offset:0x1600
	ds_read_b64_tr_b16 v[216:217], v112 offset:0x1e00
	s_waitcnt lgkmcnt(6)
	v_mfma_f32_32x32x16_bf16 v[18:33], v[108:111], v[218:221], v[18:33]
	ds_read_b64_tr_b16 v[218:219], v112 offset:0x2600
	ds_read_b64_tr_b16 v[220:221], v112 offset:0x2e00
	s_waitcnt lgkmcnt(6)
	v_mfma_f32_32x32x16_bf16 v[18:33], v[176:179], v[222:225], v[18:33]
	ds_read_b64_tr_b16 v[222:223], v112 offset:0x3600
	ds_read_b64_tr_b16 v[224:225], v112 offset:0x3e00
	s_waitcnt lgkmcnt(6)
	v_mfma_f32_32x32x16_bf16 v[2:17], v[100:103], v[180:183], v[2:17]
	v_max_f32_e32 v100, v115, v115
	v_max_f32_e32 v101, v114, v114
	v_max_f32_e32 v100, v101, v100
	v_max3_f32 v101, v116, v117, v83
	v_max3_f32 v100, v100, v82, v84
	v_max3_f32 v100, v100, v85, v118
	v_max3_f32 v101, v101, v120, v121
	s_waitcnt lgkmcnt(4)
	v_mfma_f32_32x32x16_bf16 v[2:17], v[104:107], v[214:217], v[2:17]
	v_max3_f32 v100, v100, v119, v86
	v_max3_f32 v101, v101, v88, v89
	v_max3_f32 v100, v100, v87, v122
	v_max3_f32 v101, v101, v124, v125
	v_max3_f32 v100, v100, v123, v90
	v_max3_f32 v101, v101, v92, v93
	v_max3_f32 v100, v100, v91, v126
	s_waitcnt lgkmcnt(2)
	v_mfma_f32_32x32x16_bf16 v[2:17], v[108:111], v[218:221], v[2:17]
	v_max3_f32 v101, v101, v128, v129
	v_max3_f32 v100, v100, v127, v94
	v_max3_f32 v101, v101, v96, v97
	v_max3_f32 v100, v100, v95, v101
	v_mov_b32_e32 v101, v100
	s_nop 1
	v_permlane32_swap_b32_e32 v100, v101
	s_waitcnt lgkmcnt(0)
	v_mfma_f32_32x32x16_bf16 v[2:17], v[176:179], v[222:225], v[2:17]
	v_max_f32_e32 v101, v101, v101
	v_max_f32_e32 v100, v100, v100
	v_max_f32_e32 v100, v100, v101
	v_cmp_lt_f32_e32 vcc, s40, v100
	v_mov_b32_e32 v176, 1.0
	s_cbranch_vccnz .LBB0_114
	v_cmp_gt_f32_e32 vcc, 1.0, v176
	s_cbranch_vccz .LBB0_111

; __device__ __forceinline__ void finishSM(f32x16& p0, f32x16& p1, float alpha, float& l_reg, bf16x8& pa0, bf16x8& pa1, bf16x8& pa2, bf16x8& pa3) {
; #pragma unroll
;   for (int r = 0; r < 16; ++r) p1[r] = __builtin_amdgcn_exp2f(p1[r]);
;   float ps = 0;
; #pragma unroll
;   for (int r = 0; r < 16; ++r) ps += p0[r];
; #pragma unroll
;   for (int r = 0; r < 16; ++r) ps += p1[r];
;   { auto rr = __builtin_amdgcn_permlane32_swap(__float_as_uint(ps), __float_as_uint(ps), false, false);
;     ps = __uint_as_float(rr[0]) + __uint_as_float(rr[1]); }
;   l_reg = l_reg * alpha + ps;
;     ...
;   PK4(p0, 0, pa0); PK4(p0, 8, pa1); PK4(p1, 0, pa2); PK4(p1, 8, pa3);
;     ...
; }
; template <bool MLA>
; __device__ __forceinline__ void qkt(f32x16& p0, f32x16& p1, const char* Ks, const char* KRs, const bf16x8* qr, const char* qrl, const f32x16& negm, int r32, int hi) {
; #pragma unroll
;   for (int d0 = 0; d0 < 8; ++d0) { int cb = (d0 * 16 + hi * 8) * 2;
;     bf16x8 b0 = *reinterpret_cast<const bf16x8*>(Ks + KSWZ(r32, cb));
;     bf16x8 b1 = *reinterpret_cast<const bf16x8*>(Ks + KSWZ(32 + r32, cb));
;     if (d0 == 0) { p0 = __builtin_amdgcn_mfma_f32_32x32x16_bf16(b0, qr[0], negm, 0, 0, 0); p1 = __builtin_amdgcn_mfma_f32_32x32x16_bf16(b1, qr[0], negm, 0, 0, 0); }
;     else { p0 = __builtin_amdgcn_mfma_f32_32x32x16_bf16(b0, qr[d0], p0, 0, 0, 0); p1 = __builtin_amdgcn_mfma_f32_32x32x16_bf16(b1, qr[d0], p1, 0, 0, 0); } }
.LBB0_125:
	s_mov_b32 s13, s16
	s_mov_b32 s16, s23
	s_lshl_b32 s8, s17, 14
	s_add_i32 s23, s8, 0
	s_add_i32 s32, s23, s14
	s_lshl_b32 s19, s13, 14
	s_add_i32 s8, s19, 0
	v_add_u32_e32 v98, s8, v199
	ds_read_b128 v[220:223], v98 offset:57344
	ds_read_b128 v[98:101], v98 offset:49152
	v_add_u32_e32 v201, s8, v198
	s_add_u32 vcc_lo, s2, s62
	s_addc_u32 vcc_hi, s3, s63
	s_add_i32 m0, s32, 0xc000
	v_lshl_add_u64 v[250:251], v[168:169], 0, vcc
	global_load_lds_dwordx4 v[250:251], off
	v_exp_f32_e32 v203, v82
	v_add_f32_e32 v82, 0, v217
	v_add_f32_e32 v82, v219, v82
	s_waitcnt lgkmcnt(0)
	v_mfma_f32_32x32x16_bf16 v[114:129], v[98:101], v[158:161], v[66:81]
	v_add_f32_e32 v82, v215, v82
	v_add_f32_e32 v82, v218, v82
	v_add_f32_e32 v82, v214, v82
	v_add_f32_e32 v82, v216, v82
	v_add_f32_e32 v82, v212, v82
	v_add_f32_e32 v82, v213, v82
	v_add_f32_e32 v82, v209, v82
	v_mfma_f32_32x32x16_bf16 v[98:113], v[220:223], v[158:161], v[66:81]
	ds_read_b128 v[220:223], v201 offset:57344
	ds_read_b128 v[224:227], v201 offset:49152
	v_add_u32_e32 v201, s8, v197
	s_add_u32 vcc_lo, s2, 0x1c3c1600
	s_addc_u32 vcc_hi, s3, 0
	s_mov_b32 m0, s32
	v_lshl_add_u64 v[250:251], v[0:1], 0, vcc
	global_load_lds_dwordx4 v[250:251], off
	v_add_f32_e32 v82, v211, v82
	v_add_f32_e32 v82, v208, v82
	v_add_f32_e32 v82, v210, v82
	v_add_f32_e32 v82, v205, v82
	v_add_f32_e32 v82, v207, v82
	s_waitcnt lgkmcnt(1)
	v_mfma_f32_32x32x16_bf16 v[98:113], v[220:223], v[154:157], v[98:113]
	v_add_f32_e32 v82, v204, v82
	v_add_f32_e32 v82, v206, v82
	v_add_f32_e32 v82, v203, v82
	v_exp_f32_e32 v228, v91
	v_exp_f32_e32 v229, v92
	v_exp_f32_e32 v234, v93
	v_exp_f32_e32 v235, v94
	s_waitcnt lgkmcnt(0)
	v_mfma_f32_32x32x16_bf16 v[114:129], v[224:227], v[154:157], v[114:129]
	ds_read_b128 v[220:223], v201 offset:57344
	ds_read_b128 v[224:227], v201 offset:49152
	v_add_u32_e32 v201, s8, v196
	s_add_u32 vcc_lo, s2, s62
	s_addc_u32 vcc_hi, s3, s63
	s_add_i32 m0, s32, 0xc400
	v_lshl_add_u64 v[250:251], v[170:171], 0, vcc
	global_load_lds_dwordx4 v[250:251], off
	v_exp_f32_e32 v236, v95
	v_exp_f32_e32 v237, v96
	v_exp_f32_e32 v97, v97
	s_lshl_b32 s24, s16, 14
	s_waitcnt lgkmcnt(1)
	v_mfma_f32_32x32x16_bf16 v[98:113], v[220:223], v[150:153], v[98:113]
	s_waitcnt lgkmcnt(0)
	v_mfma_f32_32x32x16_bf16 v[114:129], v[224:227], v[150:153], v[114:129]
	ds_read_b128 v[220:223], v201 offset:57344
	ds_read_b128 v[224:227], v201 offset:49152
	v_add_u32_e32 v201, s8, v195
	s_add_u32 vcc_lo, s2, 0x1c3c1680
	s_addc_u32 vcc_hi, s3, 0
	s_add_i32 m0, s32, 0x400
	v_lshl_add_u64 v[250:251], v[0:1], 0, vcc
	global_load_lds_dwordx4 v[250:251], off
	s_waitcnt lgkmcnt(1)
	v_mfma_f32_32x32x16_bf16 v[98:113], v[220:223], v[146:149], v[98:113]
	s_waitcnt lgkmcnt(0)
	v_mfma_f32_32x32x16_bf16 v[114:129], v[224:227], v[146:149], v[114:129]
	ds_read_b128 v[220:223], v201 offset:57344
	ds_read_b128 v[224:227], v201 offset:49152
	v_add_u32_e32 v201, s8, v183
	s_waitcnt lgkmcnt(1)
	v_mfma_f32_32x32x16_bf16 v[98:113], v[220:223], v[142:145], v[98:113]
	s_waitcnt lgkmcnt(0)
	v_mfma_f32_32x32x16_bf16 v[114:129], v[224:227], v[142:145], v[114:129]
	ds_read_b128 v[220:223], v201 offset:57344
	ds_read_b128 v[224:227], v201 offset:49152
	v_add_u32_e32 v201, s8, v193
	s_waitcnt lgkmcnt(1)
	v_mfma_f32_32x32x16_bf16 v[98:113], v[220:223], v[138:141], v[98:113]
	s_waitcnt lgkmcnt(0)
	v_mfma_f32_32x32x16_bf16 v[114:129], v[224:227], v[138:141], v[114:129]
	ds_read_b128 v[220:223], v201 offset:57344
	ds_read_b128 v[224:227], v201 offset:49152
	v_add_u32_e32 v201, s8, v194
	s_waitcnt lgkmcnt(1)
	v_mfma_f32_32x32x16_bf16 v[98:113], v[220:223], v[134:137], v[98:113]
	s_waitcnt lgkmcnt(0)
	v_mfma_f32_32x32x16_bf16 v[114:129], v[224:227], v[134:137], v[114:129]
	ds_read_b128 v[220:223], v201 offset:57344
	ds_read_b128 v[224:227], v201 offset:49152
	s_waitcnt lgkmcnt(1)
	v_mfma_f32_32x32x16_bf16 v[98:113], v[220:223], v[130:133], v[98:113]
	v_exp_f32_e32 v220, v83
	v_exp_f32_e32 v221, v84
	v_exp_f32_e32 v222, v85
	v_exp_f32_e32 v223, v86
	v_add_f32_e32 v82, v220, v82
	v_add_f32_e32 v82, v221, v82
	v_add_f32_e32 v82, v222, v82
	s_waitcnt lgkmcnt(0)
; template <bool FIRST, bool MLA>
; __device__ __forceinline__ void partialSM(f32x16& p0, f32x16& p1, f32x16& negm, float& m_reg, float& alpha) {
;   float a = max3f(p0[0], p0[1], p1[0]), b = max3f(p0[2], p0[3], p1[1]); a = max3f(a, p1[2], p1[3]);
; #pragma unroll
;   for (int r = 4; r < 16; r += 4) { a = max3f(a, p0[r], p0[r + 1]); b = max3f(b, p0[r + 2], p0[r + 3]); a = max3f(a, p1[r], p1[r + 1]); b = max3f(b, p1[r + 2], p1[r + 3]); }
;   float pmax = fmaxf(a, b);
;   { auto rr = __builtin_amdgcn_permlane32_swap(__float_as_uint(pmax), __float_as_uint(pmax), false, false);
;     pmax = fmaxf(__uint_as_float(rr[0]), __uint_as_float(rr[1])); }
;   alpha = 1.f;
;   if constexpr (MLA) {
;     if (FIRST) m_reg = pmax;
;     else if (!__builtin_expect(__all(pmax - m_reg <= THR2), 1)) { const float mn = fmaxf(m_reg, pmax); alpha = __builtin_amdgcn_exp2f(m_reg - mn); m_reg = mn; }
; #pragma unroll
;     for (int r = 0; r < 16; ++r) { p0[r] -= m_reg; p1[r] -= m_reg; }
;   } else
;   if (FIRST || __builtin_expect(__any(pmax > THR2), 0)) {
;     const float d = FIRST ? pmax : fmaxf(pmax, 0.f);
; #pragma unroll
;     for (int r = 0; r < 16; ++r) { p0[r] -= d; p1[r] -= d; }
; #pragma unroll
;     for (int r = 0; r < 16; ++r) negm[r] -= d;
;     asm volatile("" : "+v"(negm));
;     if (!FIRST) alpha = __builtin_amdgcn_exp2f(-d);
;   }
; #pragma unroll
;   for (int r = 0; r < 16; ++r) p0[r] = __builtin_amdgcn_exp2f(p0[r]);
; }
; __device__ __forceinline__ void finishSM(f32x16& p0, f32x16& p1, float alpha, float& l_reg, bf16x8& pa0, bf16x8& pa1, bf16x8& pa2, bf16x8& pa3) {
; #pragma unroll
;   for (int r = 0; r < 16; ++r) p1[r] = __builtin_amdgcn_exp2f(p1[r]);
;   float ps = 0;
; #pragma unroll
;   for (int r = 0; r < 16; ++r) ps += p0[r];
; #pragma unroll
;   for (int r = 0; r < 16; ++r) ps += p1[r];
;   { auto rr = __builtin_amdgcn_permlane32_swap(__float_as_uint(ps), __float_as_uint(ps), false, false);
;     ps = __uint_as_float(rr[0]) + __uint_as_float(rr[1]); }
;   l_reg = l_reg * alpha + ps;
;     ...
;   PK4(p0, 0, pa0); PK4(p0, 8, pa1); PK4(p1, 0, pa2); PK4(p1, 8, pa3);
; template <int D0> __device__ __forceinline__ void pv_one(f32x16& od, int vb, bf16x8 pa0, bf16x8 pa1, bf16x8 pa2, bf16x8 pa3) {
;   const s16x4 l0 = tr_read<v_rd_off(D0, 0, 0)>(vb), h0 = tr_read<v_rd_off(D0, 0, 1)>(vb), l1 = tr_read<v_rd_off(D0, 1, 0)>(vb), h1 = tr_read<v_rd_off(D0, 1, 1)>(vb);
	v_mfma_f32_32x32x16_bf16 v[114:129], v[224:227], v[130:133], v[114:129]
	v_exp_f32_e32 v224, v87
	v_exp_f32_e32 v225, v88
	v_exp_f32_e32 v226, v89
	v_exp_f32_e32 v227, v90
	v_add_f32_e32 v82, v223, v82
	v_add_f32_e32 v82, v224, v82
	v_add_f32_e32 v82, v225, v82
	v_add_f32_e32 v82, v226, v82
	v_add_f32_e32 v82, v227, v82
	v_add_f32_e32 v82, v228, v82
	v_add_f32_e32 v82, v229, v82
	v_add_f32_e32 v82, v234, v82
	v_add_f32_e32 v82, v235, v82
	v_add_f32_e32 v82, v236, v82
	v_add_f32_e32 v82, v237, v82
	v_add_f32_e32 v201, v97, v82
	v_cvt_pk_bf16_f32 v82, v217, v219
	v_cvt_pk_bf16_f32 v83, v215, v218
	v_cvt_pk_bf16_f32 v84, v214, v216
	v_cvt_pk_bf16_f32 v85, v212, v213
	v_cvt_pk_bf16_f32 v86, v209, v211
	v_cvt_pk_bf16_f32 v87, v208, v210
	v_cvt_pk_bf16_f32 v88, v205, v207
	v_cvt_pk_bf16_f32 v89, v204, v206
	v_cvt_pk_bf16_f32 v90, v203, v220
	v_cvt_pk_bf16_f32 v91, v221, v222
	v_cvt_pk_bf16_f32 v92, v223, v224
	v_cvt_pk_bf16_f32 v93, v225, v226
	v_cvt_pk_bf16_f32 v94, v227, v228
	v_cvt_pk_bf16_f32 v95, v229, v234
	v_cvt_pk_bf16_f32 v96, v235, v236
	v_cvt_pk_bf16_f32 v97, v237, v97
	v_add_u32_e32 v203, s24, v182
	ds_read_b64_tr_b16 v[204:205], v203 offset:0
	ds_read_b64_tr_b16 v[206:207], v203 offset:0x800
	ds_read_b64_tr_b16 v[208:209], v203 offset:0x1000
	ds_read_b64_tr_b16 v[210:211], v203 offset:0x1800
	ds_read_b64_tr_b16 v[212:213], v203 offset:0x2000
	ds_read_b64_tr_b16 v[214:215], v203 offset:0x2800
	ds_read_b64_tr_b16 v[216:217], v203 offset:0x3000
	ds_read_b64_tr_b16 v[218:219], v203 offset:0x3800
	s_waitcnt lgkmcnt(0)
	v_mov_b32_e32 v202, v201
	s_nop 1
	v_permlane32_swap_b32_e32 v201, v202
	v_permlane32_swap_b32_e32 v82, v84
	v_permlane32_swap_b32_e32 v83, v85
	v_permlane32_swap_b32_e32 v86, v88
	v_permlane32_swap_b32_e32 v87, v89
	v_permlane32_swap_b32_e32 v90, v92
	v_permlane32_swap_b32_e32 v91, v93
	v_permlane32_swap_b32_e32 v94, v96
	v_permlane32_swap_b32_e32 v95, v97
	v_mfma_f32_32x32x16_bf16 v[2:17], v[82:85], v[204:207], v[2:17]
	ds_read_b64_tr_b16 v[204:205], v203 offset:0x200
	ds_read_b64_tr_b16 v[206:207], v203 offset:0xa00
	v_mfma_f32_32x32x16_bf16 v[2:17], v[86:89], v[208:211], v[2:17]
	ds_read_b64_tr_b16 v[208:209], v203 offset:0x1200
	ds_read_b64_tr_b16 v[210:211], v203 offset:0x1a00
	v_mfma_f32_32x32x16_bf16 v[2:17], v[90:93], v[212:215], v[2:17]
	ds_read_b64_tr_b16 v[212:213], v203 offset:0x2200
	ds_read_b64_tr_b16 v[214:215], v203 offset:0x2a00
	v_mfma_f32_32x32x16_bf16 v[2:17], v[94:97], v[216:219], v[2:17]
	ds_read_b64_tr_b16 v[216:217], v203 offset:0x3200
	ds_read_b64_tr_b16 v[218:219], v203 offset:0x3a00
	s_waitcnt lgkmcnt(6)
	v_mfma_f32_32x32x16_bf16 v[50:65], v[82:85], v[204:207], v[50:65]
	ds_read_b64_tr_b16 v[204:205], v203 offset:0x400
	ds_read_b64_tr_b16 v[206:207], v203 offset:0xc00
	s_waitcnt lgkmcnt(6)
	v_mfma_f32_32x32x16_bf16 v[50:65], v[86:89], v[208:211], v[50:65]
	ds_read_b64_tr_b16 v[208:209], v203 offset:0x1400
	ds_read_b64_tr_b16 v[210:211], v203 offset:0x1c00
	s_waitcnt lgkmcnt(6)
	v_mfma_f32_32x32x16_bf16 v[50:65], v[90:93], v[212:215], v[50:65]
	ds_read_b64_tr_b16 v[212:213], v203 offset:0x2400
	ds_read_b64_tr_b16 v[214:215], v203 offset:0x2c00
	s_waitcnt lgkmcnt(6)
	v_mfma_f32_32x32x16_bf16 v[50:65], v[94:97], v[216:219], v[50:65]
	ds_read_b64_tr_b16 v[216:217], v203 offset:0x3400
	ds_read_b64_tr_b16 v[218:219], v203 offset:0x3c00
	s_waitcnt lgkmcnt(6)
	v_mfma_f32_32x32x16_bf16 v[34:49], v[82:85], v[204:207], v[34:49]
	ds_read_b64_tr_b16 v[204:205], v203 offset:0x600
	ds_read_b64_tr_b16 v[206:207], v203 offset:0xe00
	s_waitcnt lgkmcnt(6)
	v_mfma_f32_32x32x16_bf16 v[34:49], v[86:89], v[208:211], v[34:49]
	ds_read_b64_tr_b16 v[208:209], v203 offset:0x1600
	ds_read_b64_tr_b16 v[210:211], v203 offset:0x1e00
	s_waitcnt lgkmcnt(6)
	v_mfma_f32_32x32x16_bf16 v[34:49], v[90:93], v[212:215], v[34:49]
	ds_read_b64_tr_b16 v[212:213], v203 offset:0x2600
	ds_read_b64_tr_b16 v[214:215], v203 offset:0x2e00
	s_waitcnt lgkmcnt(6)
	v_mfma_f32_32x32x16_bf16 v[34:49], v[94:97], v[216:219], v[34:49]
	ds_read_b64_tr_b16 v[216:217], v203 offset:0x3600
	ds_read_b64_tr_b16 v[218:219], v203 offset:0x3e00
	s_waitcnt lgkmcnt(6)
	v_mfma_f32_32x32x16_bf16 v[18:33], v[82:85], v[204:207], v[18:33]
	v_max_f32_e32 v82, v115, v115
	v_max_f32_e32 v83, v114, v114
	v_max_f32_e32 v82, v83, v82
	v_max3_f32 v83, v116, v117, v99
	v_max3_f32 v82, v82, v98, v100
	v_max3_f32 v82, v82, v101, v118
	v_max3_f32 v83, v83, v120, v121
	s_waitcnt lgkmcnt(4)
	v_mfma_f32_32x32x16_bf16 v[18:33], v[86:89], v[208:211], v[18:33]
	v_max3_f32 v82, v82, v119, v102
	v_max3_f32 v83, v83, v104, v105
	v_max3_f32 v82, v82, v103, v122
	v_max3_f32 v83, v83, v124, v125
	v_max3_f32 v82, v82, v123, v106
	v_max3_f32 v83, v83, v108, v109
	v_max3_f32 v82, v82, v107, v126
	s_waitcnt lgkmcnt(2)
	v_mfma_f32_32x32x16_bf16 v[18:33], v[90:93], v[212:215], v[18:33]
	v_max3_f32 v83, v83, v128, v129
	v_max3_f32 v82, v82, v127, v110
	v_max3_f32 v83, v83, v112, v113
	v_max3_f32 v82, v82, v111, v83
	v_mov_b32_e32 v83, v82
	s_nop 1
	v_permlane32_swap_b32_e32 v82, v83
	s_waitcnt lgkmcnt(0)
	v_mfma_f32_32x32x16_bf16 v[18:33], v[94:97], v[216:219], v[18:33]
	v_max_f32_e32 v83, v83, v83
	v_max_f32_e32 v82, v82, v82
	v_max_f32_e32 v82, v82, v83
	v_cmp_lt_f32_e32 vcc, s40, v82
	s_cbranch_vccnz .LBB0_137
	v_mov_b32_e32 v203, 1.0
	v_cmp_gt_f32_e32 vcc, 1.0, v203
	s_cbranch_vccz .LBB0_130

; __device__ __forceinline__ void finishSM(f32x16& p0, f32x16& p1, float alpha, float& l_reg, bf16x8& pa0, bf16x8& pa1, bf16x8& pa2, bf16x8& pa3) {
; #pragma unroll
;   for (int r = 0; r < 16; ++r) p1[r] = __builtin_amdgcn_exp2f(p1[r]);
;   float ps = 0;
; #pragma unroll
;   for (int r = 0; r < 16; ++r) ps += p0[r];
; #pragma unroll
;   for (int r = 0; r < 16; ++r) ps += p1[r];
;   { auto rr = __builtin_amdgcn_permlane32_swap(__float_as_uint(ps), __float_as_uint(ps), false, false);
;     ps = __uint_as_float(rr[0]) + __uint_as_float(rr[1]); }
;   l_reg = l_reg * alpha + ps;
;     ...
;   PK4(p0, 0, pa0); PK4(p0, 8, pa1); PK4(p1, 0, pa2); PK4(p1, 8, pa3);
;     ...
; }
; template <bool MLA>
; __device__ __forceinline__ void qkt(f32x16& p0, f32x16& p1, const char* Ks, const char* KRs, const bf16x8* qr, const char* qrl, const f32x16& negm, int r32, int hi) {
; #pragma unroll
;   for (int d0 = 0; d0 < 8; ++d0) { int cb = (d0 * 16 + hi * 8) * 2;
;     bf16x8 b0 = *reinterpret_cast<const bf16x8*>(Ks + KSWZ(r32, cb));
;     bf16x8 b1 = *reinterpret_cast<const bf16x8*>(Ks + KSWZ(32 + r32, cb));
;     if (d0 == 0) { p0 = __builtin_amdgcn_mfma_f32_32x32x16_bf16(b0, qr[0], negm, 0, 0, 0); p1 = __builtin_amdgcn_mfma_f32_32x32x16_bf16(b1, qr[0], negm, 0, 0, 0); }
;     else { p0 = __builtin_amdgcn_mfma_f32_32x32x16_bf16(b0, qr[d0], p0, 0, 0, 0); p1 = __builtin_amdgcn_mfma_f32_32x32x16_bf16(b1, qr[d0], p1, 0, 0, 0); } }
.LBB0_130:
	s_waitcnt vmcnt(0)
	v_exp_f32_e32 v208, v114
	v_exp_f32_e32 v209, v115
	v_exp_f32_e32 v210, v116
	v_exp_f32_e32 v211, v117
	v_exp_f32_e32 v212, v118
	v_exp_f32_e32 v213, v119
	v_exp_f32_e32 v214, v120
	v_exp_f32_e32 v215, v121
	v_exp_f32_e32 v216, v122
	v_exp_f32_e32 v217, v123
	v_exp_f32_e32 v218, v124
	v_exp_f32_e32 v219, v125
	v_exp_f32_e32 v220, v126
	v_exp_f32_e32 v221, v127
	v_exp_f32_e32 v222, v128
	v_exp_f32_e32 v223, v129
	s_waitcnt vmcnt(0)
	s_barrier
	s_add_i32 s24, s15, s24
	v_add_u32_e32 v82, s23, v199
	ds_read_b128 v[172:175], v82 offset:57344
	ds_read_b128 v[82:85], v82 offset:49152
	v_add_u32_e32 v176, s23, v198
	s_add_u32 vcc_lo, s2, s74
	s_addc_u32 vcc_hi, s3, s75
	s_add_i32 m0, s24, 0xc000
	v_lshl_add_u64 v[250:251], v[168:169], 0, vcc
	global_load_lds_dwordx4 v[250:251], off
	v_exp_f32_e32 v177, v103
	v_exp_f32_e32 v224, v108
	v_exp_f32_e32 v225, v109
	s_waitcnt lgkmcnt(0)
	v_mfma_f32_32x32x16_bf16 v[114:129], v[82:85], v[158:161], v[66:81]
	v_exp_f32_e32 v226, v110
	v_exp_f32_e32 v227, v111
	v_exp_f32_e32 v112, v112
	v_exp_f32_e32 v113, v113
	v_mfma_f32_32x32x16_bf16 v[82:97], v[172:175], v[158:161], v[66:81]
	ds_read_b128 v[172:175], v176 offset:57344
	ds_read_b128 v[204:207], v176 offset:49152
	v_add_u32_e32 v176, s23, v197
	s_add_u32 vcc_lo, s2, 0x1c421600
	s_addc_u32 vcc_hi, s3, 0
	s_mov_b32 m0, s24
	v_lshl_add_u64 v[250:251], v[0:1], 0, vcc
	global_load_lds_dwordx4 v[250:251], off
	s_waitcnt lgkmcnt(1)
	v_mfma_f32_32x32x16_bf16 v[82:97], v[172:175], v[154:157], v[82:97]
	s_waitcnt lgkmcnt(0)
	v_mfma_f32_32x32x16_bf16 v[114:129], v[204:207], v[154:157], v[114:129]
	ds_read_b128 v[172:175], v176 offset:57344
	ds_read_b128 v[204:207], v176 offset:49152
	v_add_u32_e32 v176, s23, v196
	s_add_u32 vcc_lo, s2, s74
	s_addc_u32 vcc_hi, s3, s75
	s_add_i32 m0, s24, 0xc400
	v_lshl_add_u64 v[250:251], v[170:171], 0, vcc
	global_load_lds_dwordx4 v[250:251], off
	s_waitcnt lgkmcnt(1)
	v_mfma_f32_32x32x16_bf16 v[82:97], v[172:175], v[150:153], v[82:97]
	s_waitcnt lgkmcnt(0)
	v_mfma_f32_32x32x16_bf16 v[114:129], v[204:207], v[150:153], v[114:129]
	ds_read_b128 v[172:175], v176 offset:57344
	ds_read_b128 v[204:207], v176 offset:49152
	v_add_u32_e32 v176, s23, v195
	s_add_u32 vcc_lo, s2, 0x1c421680
	s_addc_u32 vcc_hi, s3, 0
	s_add_i32 m0, s24, 0x400
	v_lshl_add_u64 v[250:251], v[0:1], 0, vcc
	global_load_lds_dwordx4 v[250:251], off
	s_waitcnt lgkmcnt(1)
	v_mfma_f32_32x32x16_bf16 v[82:97], v[172:175], v[146:149], v[82:97]
	s_waitcnt lgkmcnt(0)
	v_mfma_f32_32x32x16_bf16 v[114:129], v[204:207], v[146:149], v[114:129]
	ds_read_b128 v[172:175], v176 offset:57344
	ds_read_b128 v[204:207], v176 offset:49152
	v_add_u32_e32 v176, s23, v183
	s_waitcnt lgkmcnt(1)
	v_mfma_f32_32x32x16_bf16 v[82:97], v[172:175], v[142:145], v[82:97]
	s_waitcnt lgkmcnt(0)
	v_mfma_f32_32x32x16_bf16 v[114:129], v[204:207], v[142:145], v[114:129]
	ds_read_b128 v[172:175], v176 offset:57344
	ds_read_b128 v[204:207], v176 offset:49152
	v_add_u32_e32 v176, s23, v193
	s_waitcnt lgkmcnt(1)
	v_mfma_f32_32x32x16_bf16 v[82:97], v[172:175], v[138:141], v[82:97]
	s_waitcnt lgkmcnt(0)
	v_mfma_f32_32x32x16_bf16 v[114:129], v[204:207], v[138:141], v[114:129]
	ds_read_b128 v[172:175], v176 offset:57344
	ds_read_b128 v[204:207], v176 offset:49152
	v_add_u32_e32 v176, s23, v194
	s_waitcnt lgkmcnt(1)
	v_mfma_f32_32x32x16_bf16 v[82:97], v[172:175], v[134:137], v[82:97]
	s_waitcnt lgkmcnt(0)
	v_mfma_f32_32x32x16_bf16 v[114:129], v[204:207], v[134:137], v[114:129]
	ds_read_b128 v[172:175], v176 offset:57344
	ds_read_b128 v[204:207], v176 offset:49152
	v_exp_f32_e32 v176, v102
	s_waitcnt lgkmcnt(1)
	v_mfma_f32_32x32x16_bf16 v[82:97], v[172:175], v[130:133], v[82:97]
	v_exp_f32_e32 v172, v98
	v_add_f32_e32 v98, 0, v208
	v_add_f32_e32 v98, v209, v98
	v_add_f32_e32 v98, v210, v98
	v_add_f32_e32 v98, v211, v98
	v_add_f32_e32 v98, v212, v98
	v_add_f32_e32 v98, v213, v98
	v_add_f32_e32 v98, v214, v98
	v_add_f32_e32 v98, v215, v98
	v_add_f32_e32 v98, v216, v98
	v_add_f32_e32 v98, v217, v98
	v_add_f32_e32 v98, v218, v98
	v_add_f32_e32 v98, v219, v98
	v_add_f32_e32 v98, v220, v98
	v_exp_f32_e32 v173, v99
	v_add_f32_e32 v98, v221, v98
	v_exp_f32_e32 v174, v100
	v_add_f32_e32 v98, v222, v98
	v_exp_f32_e32 v175, v101
	v_add_f32_e32 v98, v223, v98
	v_add_f32_e32 v98, v172, v98
	v_add_f32_e32 v98, v173, v98
	s_waitcnt lgkmcnt(0)
; template <bool FIRST, bool MLA>
; __device__ __forceinline__ void partialSM(f32x16& p0, f32x16& p1, f32x16& negm, float& m_reg, float& alpha) {
;   float a = max3f(p0[0], p0[1], p1[0]), b = max3f(p0[2], p0[3], p1[1]); a = max3f(a, p1[2], p1[3]);
; #pragma unroll
;   for (int r = 4; r < 16; r += 4) { a = max3f(a, p0[r], p0[r + 1]); b = max3f(b, p0[r + 2], p0[r + 3]); a = max3f(a, p1[r], p1[r + 1]); b = max3f(b, p1[r + 2], p1[r + 3]); }
;   float pmax = fmaxf(a, b);
;   { auto rr = __builtin_amdgcn_permlane32_swap(__float_as_uint(pmax), __float_as_uint(pmax), false, false);
;     pmax = fmaxf(__uint_as_float(rr[0]), __uint_as_float(rr[1])); }
;   alpha = 1.f;
;   if constexpr (MLA) {
;     if (FIRST) m_reg = pmax;
;     else if (!__builtin_expect(__all(pmax - m_reg <= THR2), 1)) { const float mn = fmaxf(m_reg, pmax); alpha = __builtin_amdgcn_exp2f(m_reg - mn); m_reg = mn; }
; #pragma unroll
;     for (int r = 0; r < 16; ++r) { p0[r] -= m_reg; p1[r] -= m_reg; }
;   } else
;   if (FIRST || __builtin_expect(__any(pmax > THR2), 0)) {
;     const float d = FIRST ? pmax : fmaxf(pmax, 0.f);
; #pragma unroll
;     for (int r = 0; r < 16; ++r) { p0[r] -= d; p1[r] -= d; }
; #pragma unroll
;     for (int r = 0; r < 16; ++r) negm[r] -= d;
;     asm volatile("" : "+v"(negm));
;     if (!FIRST) alpha = __builtin_amdgcn_exp2f(-d);
;   }
; #pragma unroll
;   for (int r = 0; r < 16; ++r) p0[r] = __builtin_amdgcn_exp2f(p0[r]);
; }
; __device__ __forceinline__ void finishSM(f32x16& p0, f32x16& p1, float alpha, float& l_reg, bf16x8& pa0, bf16x8& pa1, bf16x8& pa2, bf16x8& pa3) {
; #pragma unroll
;   for (int r = 0; r < 16; ++r) p1[r] = __builtin_amdgcn_exp2f(p1[r]);
;   float ps = 0;
; #pragma unroll
;   for (int r = 0; r < 16; ++r) ps += p0[r];
; #pragma unroll
;   for (int r = 0; r < 16; ++r) ps += p1[r];
;   { auto rr = __builtin_amdgcn_permlane32_swap(__float_as_uint(ps), __float_as_uint(ps), false, false);
;     ps = __uint_as_float(rr[0]) + __uint_as_float(rr[1]); }
;   l_reg = l_reg * alpha + ps;
;     ...
;   PK4(p0, 0, pa0); PK4(p0, 8, pa1); PK4(p1, 0, pa2); PK4(p1, 8, pa3);
; template <int D0> __device__ __forceinline__ void pv_one(f32x16& od, int vb, bf16x8 pa0, bf16x8 pa1, bf16x8 pa2, bf16x8 pa3) {
;   const s16x4 l0 = tr_read<v_rd_off(D0, 0, 0)>(vb), h0 = tr_read<v_rd_off(D0, 0, 1)>(vb), l1 = tr_read<v_rd_off(D0, 1, 0)>(vb), h1 = tr_read<v_rd_off(D0, 1, 1)>(vb);
	v_mfma_f32_32x32x16_bf16 v[114:129], v[204:207], v[130:133], v[114:129]
	v_exp_f32_e32 v204, v104
	v_add_f32_e32 v98, v174, v98
	v_exp_f32_e32 v205, v105
	v_add_f32_e32 v98, v175, v98
	v_exp_f32_e32 v206, v106
	v_add_f32_e32 v98, v176, v98
	v_exp_f32_e32 v207, v107
	v_add_f32_e32 v98, v177, v98
	v_add_f32_e32 v98, v204, v98
	v_add_f32_e32 v98, v205, v98
	v_add_f32_e32 v98, v206, v98
	v_add_f32_e32 v98, v207, v98
	v_add_f32_e32 v98, v224, v98
	v_add_f32_e32 v98, v225, v98
	v_add_f32_e32 v98, v226, v98
	v_add_f32_e32 v98, v227, v98
	v_add_f32_e32 v98, v112, v98
	v_cvt_pk_bf16_f32 v100, v208, v209
	v_cvt_pk_bf16_f32 v101, v210, v211
	v_cvt_pk_bf16_f32 v102, v212, v213
	v_cvt_pk_bf16_f32 v103, v214, v215
	v_cvt_pk_bf16_f32 v104, v216, v217
	v_cvt_pk_bf16_f32 v105, v218, v219
	v_cvt_pk_bf16_f32 v106, v220, v221
	v_cvt_pk_bf16_f32 v107, v222, v223
	v_cvt_pk_bf16_f32 v108, v172, v173
	v_cvt_pk_bf16_f32 v109, v174, v175
	v_cvt_pk_bf16_f32 v110, v176, v177
	v_cvt_pk_bf16_f32 v111, v204, v205
	v_cvt_pk_bf16_f32 v172, v206, v207
	v_cvt_pk_bf16_f32 v173, v224, v225
	v_cvt_pk_bf16_f32 v174, v226, v227
	v_cvt_pk_bf16_f32 v175, v112, v113
	v_add_u32_e32 v112, s19, v182
	ds_read_b64_tr_b16 v[204:205], v112 offset:0
	ds_read_b64_tr_b16 v[206:207], v112 offset:0x800
	ds_read_b64_tr_b16 v[208:209], v112 offset:0x1000
	ds_read_b64_tr_b16 v[210:211], v112 offset:0x1800
	ds_read_b64_tr_b16 v[212:213], v112 offset:0x2000
	ds_read_b64_tr_b16 v[214:215], v112 offset:0x2800
	ds_read_b64_tr_b16 v[216:217], v112 offset:0x3000
	ds_read_b64_tr_b16 v[218:219], v112 offset:0x3800
	v_add_f32_e32 v98, v113, v98
	s_waitcnt lgkmcnt(0)
	v_mov_b32_e32 v99, v98
	s_nop 1
	v_permlane32_swap_b32_e32 v98, v99
	v_permlane32_swap_b32_e32 v100, v102
	v_permlane32_swap_b32_e32 v172, v174
	v_permlane32_swap_b32_e32 v101, v103
	v_permlane32_swap_b32_e32 v104, v106
	v_permlane32_swap_b32_e32 v105, v107
	v_permlane32_swap_b32_e32 v108, v110
	v_permlane32_swap_b32_e32 v109, v111
	v_permlane32_swap_b32_e32 v173, v175
	v_mfma_f32_32x32x16_bf16 v[2:17], v[100:103], v[204:207], v[2:17]
	ds_read_b64_tr_b16 v[204:205], v112 offset:0x200
	ds_read_b64_tr_b16 v[206:207], v112 offset:0xa00
	v_mfma_f32_32x32x16_bf16 v[2:17], v[104:107], v[208:211], v[2:17]
	ds_read_b64_tr_b16 v[208:209], v112 offset:0x1200
	ds_read_b64_tr_b16 v[210:211], v112 offset:0x1a00
	v_mfma_f32_32x32x16_bf16 v[2:17], v[108:111], v[212:215], v[2:17]
	ds_read_b64_tr_b16 v[212:213], v112 offset:0x2200
	ds_read_b64_tr_b16 v[214:215], v112 offset:0x2a00
	v_mfma_f32_32x32x16_bf16 v[2:17], v[172:175], v[216:219], v[2:17]
	ds_read_b64_tr_b16 v[216:217], v112 offset:0x3200
	ds_read_b64_tr_b16 v[218:219], v112 offset:0x3a00
	s_waitcnt lgkmcnt(6)
	v_mfma_f32_32x32x16_bf16 v[50:65], v[100:103], v[204:207], v[50:65]
	ds_read_b64_tr_b16 v[204:205], v112 offset:0x400
	ds_read_b64_tr_b16 v[206:207], v112 offset:0xc00
	s_waitcnt lgkmcnt(6)
	v_mfma_f32_32x32x16_bf16 v[50:65], v[104:107], v[208:211], v[50:65]
	ds_read_b64_tr_b16 v[208:209], v112 offset:0x1400
	ds_read_b64_tr_b16 v[210:211], v112 offset:0x1c00
	s_waitcnt lgkmcnt(6)
	v_mfma_f32_32x32x16_bf16 v[50:65], v[108:111], v[212:215], v[50:65]
	ds_read_b64_tr_b16 v[212:213], v112 offset:0x2400
	ds_read_b64_tr_b16 v[214:215], v112 offset:0x2c00
	s_waitcnt lgkmcnt(6)
	v_mfma_f32_32x32x16_bf16 v[50:65], v[172:175], v[216:219], v[50:65]
	ds_read_b64_tr_b16 v[216:217], v112 offset:0x3400
	ds_read_b64_tr_b16 v[218:219], v112 offset:0x3c00
	s_waitcnt lgkmcnt(6)
	v_mfma_f32_32x32x16_bf16 v[34:49], v[100:103], v[204:207], v[34:49]
	ds_read_b64_tr_b16 v[204:205], v112 offset:0x600
	ds_read_b64_tr_b16 v[206:207], v112 offset:0xe00
	s_waitcnt lgkmcnt(6)
	v_mfma_f32_32x32x16_bf16 v[34:49], v[104:107], v[208:211], v[34:49]
	ds_read_b64_tr_b16 v[208:209], v112 offset:0x1600
	ds_read_b64_tr_b16 v[210:211], v112 offset:0x1e00
	s_waitcnt lgkmcnt(6)
	v_mfma_f32_32x32x16_bf16 v[34:49], v[108:111], v[212:215], v[34:49]
	ds_read_b64_tr_b16 v[212:213], v112 offset:0x2600
	ds_read_b64_tr_b16 v[214:215], v112 offset:0x2e00
	s_waitcnt lgkmcnt(6)
	v_mfma_f32_32x32x16_bf16 v[34:49], v[172:175], v[216:219], v[34:49]
	ds_read_b64_tr_b16 v[216:217], v112 offset:0x3600
	ds_read_b64_tr_b16 v[218:219], v112 offset:0x3e00
	s_waitcnt lgkmcnt(6)
	v_mfma_f32_32x32x16_bf16 v[18:33], v[100:103], v[204:207], v[18:33]
	v_max_f32_e32 v100, v115, v115
	v_max_f32_e32 v101, v114, v114
	v_max_f32_e32 v100, v101, v100
	v_max3_f32 v101, v116, v117, v83
	v_max3_f32 v100, v100, v82, v84
	v_max3_f32 v100, v100, v85, v118
	v_max3_f32 v101, v101, v120, v121
	s_waitcnt lgkmcnt(4)
	v_mfma_f32_32x32x16_bf16 v[18:33], v[104:107], v[208:211], v[18:33]
	v_max3_f32 v100, v100, v119, v86
	v_max3_f32 v101, v101, v88, v89
	v_max3_f32 v100, v100, v87, v122
	v_max3_f32 v101, v101, v124, v125
	v_max3_f32 v100, v100, v123, v90
	v_max3_f32 v101, v101, v92, v93
	v_max3_f32 v100, v100, v91, v126
	s_waitcnt lgkmcnt(2)
	v_mfma_f32_32x32x16_bf16 v[18:33], v[108:111], v[212:215], v[18:33]
	v_max3_f32 v101, v101, v128, v129
	v_max3_f32 v100, v100, v127, v94
	v_max3_f32 v101, v101, v96, v97
	v_max3_f32 v100, v100, v95, v101
	v_mov_b32_e32 v101, v100
	s_nop 1
	v_permlane32_swap_b32_e32 v100, v101
	s_waitcnt lgkmcnt(0)
	v_mfma_f32_32x32x16_bf16 v[18:33], v[172:175], v[216:219], v[18:33]
	v_max_f32_e32 v101, v101, v101
	v_max_f32_e32 v100, v100, v100
	v_max_f32_e32 v100, v100, v101
	v_cmp_lt_f32_e32 vcc, s40, v100
	v_mov_b32_e32 v172, 1.0
	s_cbranch_vccnz .LBB0_138
	v_cmp_gt_f32_e32 vcc, 1.0, v172
	s_cbranch_vccz .LBB0_135
